# grid barrier: non-leader WGs poll the cross-XCD release word directly (one hop less)
# baseline (speedup 1.0000x reference)
.LBB0_69:
	s_or_b64 exec, exec, s[10:11]
	v_cvt_f32_u32_e32 v4, v2
	s_waitcnt vmcnt(0)
	v_readfirstlane_b32 s6, v3
	v_sub_u32_e32 v3, 0, v2
	v_rcp_iflag_f32_e32 v4, v4
	v_add_u32_e32 v5, s6, v1
	v_mul_f32_e32 v4, 0x4f7ffffe, v4
	v_cvt_u32_f32_e32 v4, v4
	v_mul_lo_u32 v1, v3, v4
	v_mul_hi_u32 v1, v4, v1
	v_add_u32_e32 v1, v4, v1
	v_mul_hi_u32 v1, v5, v1
	v_mul_lo_u32 v3, v1, v2
	v_sub_u32_e32 v3, v5, v3
	v_add_u32_e32 v4, 1, v1
	v_cmp_ge_u32_e32 vcc, v3, v2
	s_nop 1
	v_cndmask_b32_e32 v1, v1, v4, vcc
	v_sub_u32_e32 v4, v3, v2
	v_cndmask_b32_e32 v3, v3, v4, vcc
	v_add_u32_e32 v4, 1, v1
	v_cmp_ge_u32_e32 vcc, v3, v2
	v_add_u32_e32 v3, 1, v5
	s_nop 0
	v_cndmask_b32_e32 v1, v1, v4, vcc
	v_mul_lo_u32 v4, v2, v1
	v_add_u32_e32 v2, v4, v2
	v_cmp_ne_u32_e32 vcc, v3, v2
	s_and_saveexec_b64 s[6:7], vcc
	s_xor_b64 s[6:7], exec, s[6:7]
	s_cbranch_execz .LBB0_83
	s_waitcnt lgkmcnt(0)
	v_mov_b32_e32 v0, 0x3b100
	global_load_dword v0, v0, s[30:31] offset:1024 sc1
	s_add_u32 s14, s30, 0x3b500
	s_addc_u32 s15, s31, 0
	s_waitcnt vmcnt(0)
	v_cmp_eq_u32_e32 vcc, v0, v1
	s_and_saveexec_b64 s[10:11], vcc
	s_cbranch_execz .LBB0_82
	s_add_u32 s12, s30, 0x38200
	s_addc_u32 s13, s31, 0
	s_mov_b32 s26, 1
	s_mov_b64 s[16:17], 0
	v_mov_b32_e32 v0, 0
	s_branch .LBB0_73

.LBB0_411:
	s_or_b64 exec, exec, s[6:7]
	v_cvt_f32_u32_e32 v4, v2
	s_waitcnt vmcnt(0)
	v_readfirstlane_b32 s4, v3
	v_sub_u32_e32 v3, 0, v2
	v_rcp_iflag_f32_e32 v4, v4
	v_add_u32_e32 v5, s4, v1
	v_mul_f32_e32 v4, 0x4f7ffffe, v4
	v_cvt_u32_f32_e32 v4, v4
	v_mul_lo_u32 v1, v3, v4
	v_mul_hi_u32 v1, v4, v1
	v_add_u32_e32 v1, v4, v1
	v_mul_hi_u32 v1, v5, v1
	v_mul_lo_u32 v3, v1, v2
	v_sub_u32_e32 v3, v5, v3
	v_add_u32_e32 v4, 1, v1
	v_cmp_ge_u32_e32 vcc, v3, v2
	s_nop 1
	v_cndmask_b32_e32 v1, v1, v4, vcc
	v_sub_u32_e32 v4, v3, v2
	v_cndmask_b32_e32 v3, v3, v4, vcc
	v_add_u32_e32 v4, 1, v1
	v_cmp_ge_u32_e32 vcc, v3, v2
	v_add_u32_e32 v3, 1, v5
	s_nop 0
	v_cndmask_b32_e32 v1, v1, v4, vcc
	v_mul_lo_u32 v4, v2, v1
	v_add_u32_e32 v2, v4, v2
	v_cmp_ne_u32_e32 vcc, v3, v2
	s_and_saveexec_b64 s[4:5], vcc
	s_xor_b64 s[4:5], exec, s[4:5]
	s_cbranch_execz .LBB0_425
	s_waitcnt lgkmcnt(0)
	v_mov_b32_e32 v0, 0x3b100
	global_load_dword v0, v0, s[30:31] offset:1024 sc1
	s_add_u32 s12, s30, 0x3b500
	s_addc_u32 s13, s31, 0
	s_waitcnt vmcnt(0)
	v_cmp_eq_u32_e32 vcc, v0, v1
	s_and_saveexec_b64 s[6:7], vcc
	s_cbranch_execz .LBB0_424
	s_add_u32 s10, s30, 0x38200
	s_addc_u32 s11, s31, 0
	s_mov_b32 s24, 1
	s_mov_b64 s[14:15], 0
	v_mov_b32_e32 v0, 0
	s_branch .LBB0_415
